# chained MFMA order + proj/ffn_in keep the wave-half offset across units (leading half's epilogue overlaps trailing half's last MFMA block)
# baseline (speedup 1.0000x reference)
; #define PG8_STAGE(bufoff, gbase, voff) do { const char* gb_ = (const char*)(gbase); asm volatile("" : "+s"(gb_)); _Pragma("unroll") for (int _i = 0; _i < 2; ++_i) { unsigned vo_ = (voff)[_i]; asm volatile("" : "+v"(vo_));        \
;         __builtin_amdgcn_global_load_lds((const unsigned*)(gb_ + vo_), (PG8_LAS unsigned*)(lds + (bufoff) + ldsw + _i * 8192), 16, 0, 0); } } while (0)
; #define PG8_LDA(dst, b, h) do { _Pragma("unroll") for (int m = 0; m < 4; ++m) _Pragma("unroll") for (int k = 0; k < 2; ++k) dst[m][k] = *(const PG8_LAS bf16x8*)(lds + PG8_SA(b, h) + aoff + m * 2048 + k * 1024); } while (0)
; #define PG8_LDB(dst, b, h) do { _Pragma("unroll") for (int n = 0; n < 2; ++n) _Pragma("unroll") for (int k = 0; k < 2; ++k) dst[n][k] = *(const PG8_LAS bf16x8*)(lds + PG8_SB(b, h) + boff + n * 2048 + k * 1024); } while (0)
; #define PG8_MMA(ai, bj, At, Bt) do { __builtin_amdgcn_s_setprio(1); _Pragma("unroll") for (int m = 0; m < 4; ++m) _Pragma("unroll") for (int n = 0; n < 2; ++n) _Pragma("unroll") for (int k = 0; k < 2; ++k) \
;         acc[ai][bj][m][n] = __builtin_amdgcn_mfma_f32_16x16x32_bf16(Bt[n][k], At[m][k], acc[ai][bj][m][n], 0, 0, 0); __builtin_amdgcn_s_setprio(0); } while (0)
; #define PG8_WAIT_V(n) asm volatile("s_waitcnt vmcnt(" #n ")" ::: "memory")
; template <class Epi, class Sched, bool ALIGN_EPI = false, bool SP2 = false>
; __device__ __forceinline__ void gemm_phase(PG8_LAS unsigned char* lds, const Gemm g, const Sched& S, const Epi& E) {
;     ...
;             const bool last = (t == nt - 2);
;             const char* a1 = cA + (size_t)(t + 1) * kstep;
;             const char* a2 = last ? nA : cA + (size_t)(t + 2) * kstep; const char* b2 = last ? nB : cB + (size_t)(t + 2) * kstep;
;             const char* a3 = a2 + kstep; const char* b3 = b2 + kstep;
;             if (last && has_next) S.a_ready(nxt);
;             if constexpr (SP2) {
;             PG8_LDB(B0, 0, 0); PG8_LDB(B1, 0, 1); PG8_SCHED; PG8_LDA(At, 0, 0); PG8_STAGE(PG8_SA(1, 1), a1 + hstep, voffA);
;             PG8_WAIT_V(8); PG8_WAIT_L(0); PG8_BAR; PG8_MMA(0, 0, At, B0); PG8_MMA(0, 1, At, B1); PG8_BAR; PG8_SCHED;
;             PG8_LDA(At, 0, 1); PG8_STAGE(PG8_SB(0, 0), b2, voffB); PG8_STAGE(PG8_SB(0, 1), b2 + hstep, voffB); PG8_STAGE(PG8_SA(0, 0), a2, voffA);
;             PG8_WAIT_V(8); PG8_WAIT_L(0); PG8_BAR; PG8_MMA(1, 0, At, B0); PG8_MMA(1, 1, At, B1); PG8_BAR; PG8_SCHED;
.LBB0_232:
	s_add_u32 s2, s0, 0x100
	s_addc_u32 s3, s1, 0
	s_cmp_eq_u32 s30, 28
	s_cselect_b32 s10, s25, s2
	s_cselect_b32 s11, s24, s3
	s_cselect_b32 s8, s27, s28
	s_cselect_b32 s9, s26, s29
	s_add_u32 s6, s10, 0x80
	s_addc_u32 s7, s11, 0
	s_add_i32 s31, 0, 0x10000
	s_add_i32 s33, 0, 0x14000
	ds_read_b128 v[66:69], v244
	ds_read_b128 v[70:73], v244 offset:1024
	ds_read_b128 v[74:77], v244 offset:2048
	ds_read_b128 v[78:81], v244 offset:3072
	ds_read_b128 v[146:149], v244 offset:16384
	ds_read_b128 v[150:153], v244 offset:17408
	ds_read_b128 v[154:157], v244 offset:18432
	ds_read_b128 v[158:161], v244 offset:19456
	s_add_u32 s0, s0, 0x80080
	s_addc_u32 s1, s1, 0
	ds_read_b128 v[178:181], v223
	ds_read_b128 v[182:185], v223 offset:1024
	ds_read_b128 v[192:195], v223 offset:2048
	ds_read_b128 v[196:199], v223 offset:3072
	ds_read_b128 v[200:203], v223 offset:4096
	ds_read_b128 v[204:207], v223 offset:5120
	ds_read_b128 v[208:211], v223 offset:6144
	ds_read_b128 v[212:215], v223 offset:7168
	s_add_i32 m0, s13, 0xc000
	s_nop 0
	global_load_lds_dwordx4 v1, s[0:1]
	s_add_i32 m0, s13, 0xe000
	s_nop 0
	global_load_lds_dwordx4 v191, s[0:1]
	s_waitcnt vmcnt(8)
	s_waitcnt lgkmcnt(0)
	s_barrier
	s_setprio 1
	s_waitcnt lgkmcnt(0)
	v_mfma_f32_16x16x32_bf16 v[142:145], v[66:69], v[178:181], v[142:145]
	v_mfma_f32_16x16x32_bf16 v[142:145], v[70:73], v[182:185], v[142:145]
	v_mfma_f32_16x16x32_bf16 v[134:137], v[66:69], v[192:195], v[134:137]
	v_mfma_f32_16x16x32_bf16 v[134:137], v[70:73], v[196:199], v[134:137]
	v_mfma_f32_16x16x32_bf16 v[126:129], v[66:69], v[200:203], v[126:129]
	v_mfma_f32_16x16x32_bf16 v[126:129], v[70:73], v[204:207], v[126:129]
	v_mfma_f32_16x16x32_bf16 v[118:121], v[66:69], v[208:211], v[118:121]
	v_mfma_f32_16x16x32_bf16 v[118:121], v[70:73], v[212:215], v[118:121]
	v_mfma_f32_16x16x32_bf16 v[138:141], v[74:77], v[178:181], v[138:141]
	v_mfma_f32_16x16x32_bf16 v[138:141], v[78:81], v[182:185], v[138:141]
	v_mfma_f32_16x16x32_bf16 v[130:133], v[74:77], v[192:195], v[130:133]
	v_mfma_f32_16x16x32_bf16 v[130:133], v[78:81], v[196:199], v[130:133]
	v_mfma_f32_16x16x32_bf16 v[122:125], v[74:77], v[200:203], v[122:125]
	v_mfma_f32_16x16x32_bf16 v[122:125], v[78:81], v[204:207], v[122:125]
	v_mfma_f32_16x16x32_bf16 v[114:117], v[74:77], v[208:211], v[114:117]
	v_mfma_f32_16x16x32_bf16 v[114:117], v[78:81], v[212:215], v[114:117]
	s_setprio 0
	s_setprio 1
	v_mfma_f32_16x16x32_bf16 v[62:65], v[146:149], v[178:181], v[62:65]
	v_mfma_f32_16x16x32_bf16 v[62:65], v[150:153], v[182:185], v[62:65]
	v_mfma_f32_16x16x32_bf16 v[54:57], v[146:149], v[192:195], v[54:57]
	v_mfma_f32_16x16x32_bf16 v[54:57], v[150:153], v[196:199], v[54:57]
	v_mfma_f32_16x16x32_bf16 v[46:49], v[146:149], v[200:203], v[46:49]
	v_mfma_f32_16x16x32_bf16 v[46:49], v[150:153], v[204:207], v[46:49]
	v_mfma_f32_16x16x32_bf16 v[38:41], v[146:149], v[208:211], v[38:41]
	v_mfma_f32_16x16x32_bf16 v[38:41], v[150:153], v[212:215], v[38:41]
	v_mfma_f32_16x16x32_bf16 v[58:61], v[154:157], v[178:181], v[58:61]
	v_mfma_f32_16x16x32_bf16 v[58:61], v[158:161], v[182:185], v[58:61]
	v_mfma_f32_16x16x32_bf16 v[50:53], v[154:157], v[192:195], v[50:53]
	v_mfma_f32_16x16x32_bf16 v[50:53], v[158:161], v[196:199], v[50:53]
	v_mfma_f32_16x16x32_bf16 v[42:45], v[154:157], v[200:203], v[42:45]
	v_mfma_f32_16x16x32_bf16 v[42:45], v[158:161], v[204:207], v[42:45]
	v_mfma_f32_16x16x32_bf16 v[34:37], v[154:157], v[208:211], v[34:37]
	v_mfma_f32_16x16x32_bf16 v[34:37], v[158:161], v[212:215], v[34:37]
	s_setprio 0
	s_barrier
	s_mov_b64 s[0:1], s[8:9]
	s_add_i32 s31, s31, s12
	ds_read_b128 v[178:181], v223 offset:16384
	ds_read_b128 v[182:185], v223 offset:17408
	ds_read_b128 v[192:195], v223 offset:18432
	ds_read_b128 v[196:199], v223 offset:19456
	ds_read_b128 v[200:203], v223 offset:20480
	ds_read_b128 v[204:207], v223 offset:21504
	ds_read_b128 v[208:211], v223 offset:22528
	ds_read_b128 v[212:215], v223 offset:23552
	s_mov_b32 m0, s31
	s_nop 0
	global_load_lds_dwordx4 v189, s[0:1]
	s_add_i32 m0, s31, 0x2000
	s_nop 0
	global_load_lds_dwordx4 v219, s[0:1]
	s_add_u32 s0, s8, 0x80000
	s_addc_u32 s1, s9, 0
	s_add_i32 s31, s33, s12
	s_mov_b32 m0, s31
	s_nop 0
	global_load_lds_dwordx4 v189, s[0:1]
	s_add_i32 m0, s31, 0x2000
	s_nop 0
	global_load_lds_dwordx4 v219, s[0:1]
	s_mov_b64 s[0:1], s[10:11]
	s_mov_b32 m0, s13
	s_nop 0
	global_load_lds_dwordx4 v1, s[0:1]
	s_mov_b32 m0, s14
	s_nop 0
	global_load_lds_dwordx4 v191, s[0:1]
	s_waitcnt vmcnt(8)
	s_waitcnt lgkmcnt(0)
	s_barrier
	s_setprio 1
	s_waitcnt lgkmcnt(0)
	v_mfma_f32_16x16x32_bf16 v[110:113], v[66:69], v[178:181], v[110:113]
	v_mfma_f32_16x16x32_bf16 v[110:113], v[70:73], v[182:185], v[110:113]
	v_mfma_f32_16x16x32_bf16 v[102:105], v[66:69], v[192:195], v[102:105]
	v_mfma_f32_16x16x32_bf16 v[102:105], v[70:73], v[196:199], v[102:105]
	v_mfma_f32_16x16x32_bf16 v[94:97], v[66:69], v[200:203], v[94:97]
	v_mfma_f32_16x16x32_bf16 v[94:97], v[70:73], v[204:207], v[94:97]
	v_mfma_f32_16x16x32_bf16 v[66:69], v[66:69], v[208:211], v[86:89]
	v_mfma_f32_16x16x32_bf16 v[66:69], v[70:73], v[212:215], v[66:69]
	v_mfma_f32_16x16x32_bf16 v[106:109], v[74:77], v[178:181], v[106:109]
	v_mfma_f32_16x16x32_bf16 v[106:109], v[78:81], v[182:185], v[106:109]
	v_mfma_f32_16x16x32_bf16 v[98:101], v[74:77], v[192:195], v[98:101]
	v_mfma_f32_16x16x32_bf16 v[98:101], v[78:81], v[196:199], v[98:101]
	v_mfma_f32_16x16x32_bf16 v[90:93], v[74:77], v[200:203], v[90:93]
	v_mfma_f32_16x16x32_bf16 v[90:93], v[78:81], v[204:207], v[90:93]
	v_mfma_f32_16x16x32_bf16 v[70:73], v[74:77], v[208:211], v[82:85]
	v_mfma_f32_16x16x32_bf16 v[70:73], v[78:81], v[212:215], v[70:73]
	s_setprio 0
	s_setprio 1
	v_mfma_f32_16x16x32_bf16 v[30:33], v[146:149], v[178:181], v[30:33]
	v_mfma_f32_16x16x32_bf16 v[30:33], v[150:153], v[182:185], v[30:33]
	v_mfma_f32_16x16x32_bf16 v[22:25], v[146:149], v[192:195], v[22:25]
	v_mfma_f32_16x16x32_bf16 v[22:25], v[150:153], v[196:199], v[22:25]
	v_mfma_f32_16x16x32_bf16 v[14:17], v[146:149], v[200:203], v[14:17]
	v_mfma_f32_16x16x32_bf16 v[14:17], v[150:153], v[204:207], v[14:17]
	v_mfma_f32_16x16x32_bf16 v[6:9], v[146:149], v[208:211], v[6:9]
	v_mfma_f32_16x16x32_bf16 v[6:9], v[150:153], v[212:215], v[6:9]
	v_mfma_f32_16x16x32_bf16 v[26:29], v[154:157], v[178:181], v[26:29]
	v_mfma_f32_16x16x32_bf16 v[26:29], v[158:161], v[182:185], v[26:29]
	v_mfma_f32_16x16x32_bf16 v[18:21], v[154:157], v[192:195], v[18:21]
	v_mfma_f32_16x16x32_bf16 v[18:21], v[158:161], v[196:199], v[18:21]
	v_mfma_f32_16x16x32_bf16 v[10:13], v[154:157], v[200:203], v[10:13]
	v_mfma_f32_16x16x32_bf16 v[10:13], v[158:161], v[204:207], v[10:13]
	v_mfma_f32_16x16x32_bf16 v[2:5], v[154:157], v[208:211], v[2:5]
	v_mfma_f32_16x16x32_bf16 v[2:5], v[158:161], v[212:215], v[2:5]
	s_setprio 0
	s_barrier
; #define PG8_STAGE(bufoff, gbase, voff) do { const char* gb_ = (const char*)(gbase); asm volatile("" : "+s"(gb_)); _Pragma("unroll") for (int _i = 0; _i < 2; ++_i) { unsigned vo_ = (voff)[_i]; asm volatile("" : "+v"(vo_));        \
;         __builtin_amdgcn_global_load_lds((const unsigned*)(gb_ + vo_), (PG8_LAS unsigned*)(lds + (bufoff) + ldsw + _i * 8192), 16, 0, 0); } } while (0)
; #define PG8_LDA(dst, b, h) do { _Pragma("unroll") for (int m = 0; m < 4; ++m) _Pragma("unroll") for (int k = 0; k < 2; ++k) dst[m][k] = *(const PG8_LAS bf16x8*)(lds + PG8_SA(b, h) + aoff + m * 2048 + k * 1024); } while (0)
; #define PG8_LDB(dst, b, h) do { _Pragma("unroll") for (int n = 0; n < 2; ++n) _Pragma("unroll") for (int k = 0; k < 2; ++k) dst[n][k] = *(const PG8_LAS bf16x8*)(lds + PG8_SB(b, h) + boff + n * 2048 + k * 1024); } while (0)
; #define PG8_MMA(ai, bj, At, Bt) do { __builtin_amdgcn_s_setprio(1); _Pragma("unroll") for (int m = 0; m < 4; ++m) _Pragma("unroll") for (int n = 0; n < 2; ++n) _Pragma("unroll") for (int k = 0; k < 2; ++k) \
;         acc[ai][bj][m][n] = __builtin_amdgcn_mfma_f32_16x16x32_bf16(Bt[n][k], At[m][k], acc[ai][bj][m][n], 0, 0, 0); __builtin_amdgcn_s_setprio(0); } while (0)
; #define PG8_WAIT_V(n) asm volatile("s_waitcnt vmcnt(" #n ")" ::: "memory")
; #define PG8_WAIT_L(n) asm volatile("s_waitcnt lgkmcnt(" #n ")" ::: "memory")
; #define PG8_BAR __builtin_amdgcn_s_barrier()
; #define PG8_SCHED __builtin_amdgcn_sched_barrier(0)
; template <class Epi, class Sched, bool ALIGN_EPI = false, bool SP2 = false>
; __device__ __forceinline__ void gemm_phase(PG8_LAS unsigned char* lds, const Gemm g, const Sched& S, const Epi& E) {
;     ...
;             PG8_LDB(B0, 1, 0); PG8_LDB(B1, 1, 1); PG8_SCHED; PG8_LDA(At, 1, 0); PG8_STAGE(PG8_SA(0, 1), a2 + hstep, voffA);
;             PG8_WAIT_V(8); PG8_WAIT_L(0); PG8_BAR; PG8_MMA(0, 0, At, B0); PG8_MMA(0, 1, At, B1); PG8_BAR; PG8_SCHED;
;             PG8_LDA(At, 1, 1); PG8_STAGE(PG8_SB(1, 0), b3, voffB); PG8_STAGE(PG8_SB(1, 1), b3 + hstep, voffB); PG8_STAGE(PG8_SA(1, 0), a3, voffA);
;             PG8_WAIT_V(8); PG8_WAIT_L(0); PG8_BAR; PG8_MMA(1, 0, At, B0); PG8_MMA(1, 1, At, B1); PG8_BAR; PG8_SCHED;
	s_add_i32 s31, 0, 0x18000
	s_add_i32 s33, 0, 0x1c000
	ds_read_b128 v[74:77], v244 offset:32768
	ds_read_b128 v[78:81], v244 offset:33792
	ds_read_b128 v[82:85], v244 offset:34816
	ds_read_b128 v[146:149], v244 offset:35840
	ds_read_b128 v[150:153], v244 offset:49152
	ds_read_b128 v[154:157], v244 offset:50176
	ds_read_b128 v[158:161], v244 offset:51200
	ds_read_b128 v[178:181], v244 offset:52224
	s_add_u32 s0, s10, 0x80000
	s_addc_u32 s1, s11, 0
	s_mov_b32 m0, s15
	ds_read_b128 v[86:89], v223 offset:32768
	ds_read_b128 v[182:185], v223 offset:33792
	ds_read_b128 v[192:195], v223 offset:34816
	ds_read_b128 v[196:199], v223 offset:35840
	ds_read_b128 v[200:203], v223 offset:36864
	ds_read_b128 v[204:207], v223 offset:37888
	ds_read_b128 v[208:211], v223 offset:38912
	ds_read_b128 v[212:215], v223 offset:39936
	s_nop 0
	global_load_lds_dwordx4 v1, s[0:1]
	s_mov_b32 m0, s16
	s_nop 0
	global_load_lds_dwordx4 v191, s[0:1]
	s_waitcnt vmcnt(8)
	s_waitcnt lgkmcnt(0)
	s_barrier
	s_setprio 1
	s_waitcnt lgkmcnt(0)
	v_mfma_f32_16x16x32_bf16 v[142:145], v[74:77], v[86:89], v[142:145]
	v_mfma_f32_16x16x32_bf16 v[142:145], v[78:81], v[182:185], v[142:145]
	v_mfma_f32_16x16x32_bf16 v[134:137], v[74:77], v[192:195], v[134:137]
	v_mfma_f32_16x16x32_bf16 v[134:137], v[78:81], v[196:199], v[134:137]
	v_mfma_f32_16x16x32_bf16 v[126:129], v[74:77], v[200:203], v[126:129]
	v_mfma_f32_16x16x32_bf16 v[126:129], v[78:81], v[204:207], v[126:129]
	v_mfma_f32_16x16x32_bf16 v[118:121], v[74:77], v[208:211], v[118:121]
	v_mfma_f32_16x16x32_bf16 v[118:121], v[78:81], v[212:215], v[118:121]
	v_mfma_f32_16x16x32_bf16 v[138:141], v[82:85], v[86:89], v[138:141]
	v_mfma_f32_16x16x32_bf16 v[138:141], v[146:149], v[182:185], v[138:141]
	v_mfma_f32_16x16x32_bf16 v[130:133], v[82:85], v[192:195], v[130:133]
	v_mfma_f32_16x16x32_bf16 v[130:133], v[146:149], v[196:199], v[130:133]
	v_mfma_f32_16x16x32_bf16 v[122:125], v[82:85], v[200:203], v[122:125]
	v_mfma_f32_16x16x32_bf16 v[122:125], v[146:149], v[204:207], v[122:125]
	v_mfma_f32_16x16x32_bf16 v[114:117], v[82:85], v[208:211], v[114:117]
	v_mfma_f32_16x16x32_bf16 v[114:117], v[146:149], v[212:215], v[114:117]
	s_setprio 0
	s_setprio 1
	v_mfma_f32_16x16x32_bf16 v[62:65], v[150:153], v[86:89], v[62:65]
	v_mfma_f32_16x16x32_bf16 v[62:65], v[154:157], v[182:185], v[62:65]
	v_mfma_f32_16x16x32_bf16 v[54:57], v[150:153], v[192:195], v[54:57]
	v_mfma_f32_16x16x32_bf16 v[54:57], v[154:157], v[196:199], v[54:57]
	v_mfma_f32_16x16x32_bf16 v[46:49], v[150:153], v[200:203], v[46:49]
	v_mfma_f32_16x16x32_bf16 v[46:49], v[154:157], v[204:207], v[46:49]
	v_mfma_f32_16x16x32_bf16 v[38:41], v[150:153], v[208:211], v[38:41]
	v_mfma_f32_16x16x32_bf16 v[38:41], v[154:157], v[212:215], v[38:41]
	v_mfma_f32_16x16x32_bf16 v[58:61], v[158:161], v[86:89], v[58:61]
	v_mfma_f32_16x16x32_bf16 v[58:61], v[178:181], v[182:185], v[58:61]
	v_mfma_f32_16x16x32_bf16 v[50:53], v[158:161], v[192:195], v[50:53]
	v_mfma_f32_16x16x32_bf16 v[50:53], v[178:181], v[196:199], v[50:53]
	v_mfma_f32_16x16x32_bf16 v[42:45], v[158:161], v[200:203], v[42:45]
	v_mfma_f32_16x16x32_bf16 v[42:45], v[178:181], v[204:207], v[42:45]
	v_mfma_f32_16x16x32_bf16 v[34:37], v[158:161], v[208:211], v[34:37]
	v_mfma_f32_16x16x32_bf16 v[34:37], v[178:181], v[212:215], v[34:37]
	s_setprio 0
	s_barrier
	s_add_u32 s0, s8, 0x80
	s_addc_u32 s1, s9, 0
	s_add_i32 s10, s31, s12
	ds_read_b128 v[182:185], v223 offset:49152
	ds_read_b128 v[192:195], v223 offset:50176
	ds_read_b128 v[196:199], v223 offset:51200
	ds_read_b128 v[200:203], v223 offset:52224
	ds_read_b128 v[204:207], v223 offset:53248
	ds_read_b128 v[208:211], v223 offset:54272
	ds_read_b128 v[212:215], v223 offset:55296
	ds_read_b128 v[224:227], v223 offset:56320
	s_mov_b32 m0, s10
	s_nop 0
	global_load_lds_dwordx4 v189, s[0:1]
	s_add_i32 m0, s10, 0x2000
	s_nop 0
	global_load_lds_dwordx4 v219, s[0:1]
	s_add_u32 s0, s8, 0x80080
	s_addc_u32 s1, s9, 0
	s_add_i32 s8, s33, s12
	s_mov_b32 m0, s8
	s_nop 0
	global_load_lds_dwordx4 v189, s[0:1]
	s_add_i32 m0, s8, 0x2000
	s_nop 0
	global_load_lds_dwordx4 v219, s[0:1]
	s_mov_b32 m0, s19
	s_nop 0
	global_load_lds_dwordx4 v1, s[6:7]
	s_mov_b32 m0, s20
	s_nop 0
	global_load_lds_dwordx4 v191, s[6:7]
	s_waitcnt vmcnt(8)
	s_waitcnt lgkmcnt(0)
	s_barrier
	s_setprio 1
	s_waitcnt lgkmcnt(0)
	v_mfma_f32_16x16x32_bf16 v[86:89], v[74:77], v[182:185], v[110:113]
	v_mfma_f32_16x16x32_bf16 v[110:113], v[78:81], v[192:195], v[86:89]
	v_mfma_f32_16x16x32_bf16 v[66:69], v[74:77], v[212:215], v[66:69]
	v_mfma_f32_16x16x32_bf16 v[86:89], v[82:85], v[182:185], v[106:109]
	v_mfma_f32_16x16x32_bf16 v[106:109], v[146:149], v[192:195], v[86:89]
	v_mfma_f32_16x16x32_bf16 v[86:89], v[74:77], v[196:199], v[102:105]
	v_mfma_f32_16x16x32_bf16 v[102:105], v[78:81], v[200:203], v[86:89]
	v_mfma_f32_16x16x32_bf16 v[86:89], v[82:85], v[196:199], v[98:101]
	v_mfma_f32_16x16x32_bf16 v[98:101], v[146:149], v[200:203], v[86:89]
	v_mfma_f32_16x16x32_bf16 v[86:89], v[74:77], v[204:207], v[94:97]
	v_mfma_f32_16x16x32_bf16 v[94:97], v[78:81], v[208:211], v[86:89]
	v_mfma_f32_16x16x32_bf16 v[86:89], v[82:85], v[204:207], v[90:93]
	v_mfma_f32_16x16x32_bf16 v[90:93], v[146:149], v[208:211], v[86:89]
	v_mfma_f32_16x16x32_bf16 v[86:89], v[78:81], v[224:227], v[66:69]
	v_mfma_f32_16x16x32_bf16 v[66:69], v[82:85], v[212:215], v[70:73]
	v_mfma_f32_16x16x32_bf16 v[82:85], v[146:149], v[224:227], v[66:69]
	s_setprio 0
	s_setprio 1
	v_mfma_f32_16x16x32_bf16 v[30:33], v[150:153], v[182:185], v[30:33]
	v_mfma_f32_16x16x32_bf16 v[30:33], v[154:157], v[192:195], v[30:33]
	v_mfma_f32_16x16x32_bf16 v[22:25], v[150:153], v[196:199], v[22:25]
	v_mfma_f32_16x16x32_bf16 v[22:25], v[154:157], v[200:203], v[22:25]
	v_mfma_f32_16x16x32_bf16 v[14:17], v[150:153], v[204:207], v[14:17]
	v_mfma_f32_16x16x32_bf16 v[14:17], v[154:157], v[208:211], v[14:17]
	v_mfma_f32_16x16x32_bf16 v[6:9], v[150:153], v[212:215], v[6:9]
	v_mfma_f32_16x16x32_bf16 v[6:9], v[154:157], v[224:227], v[6:9]
	v_mfma_f32_16x16x32_bf16 v[26:29], v[158:161], v[182:185], v[26:29]
	v_mfma_f32_16x16x32_bf16 v[26:29], v[178:181], v[192:195], v[26:29]
	v_mfma_f32_16x16x32_bf16 v[18:21], v[158:161], v[196:199], v[18:21]
	v_mfma_f32_16x16x32_bf16 v[18:21], v[178:181], v[200:203], v[18:21]
	v_mfma_f32_16x16x32_bf16 v[10:13], v[158:161], v[204:207], v[10:13]
	v_mfma_f32_16x16x32_bf16 v[10:13], v[178:181], v[208:211], v[10:13]
	v_mfma_f32_16x16x32_bf16 v[2:5], v[158:161], v[212:215], v[2:5]
	v_mfma_f32_16x16x32_bf16 v[2:5], v[178:181], v[224:227], v[2:5]
	s_setprio 0
	s_barrier
	s_add_i32 s30, s30, 2
	s_add_u32 s28, s28, 0x100
	s_addc_u32 s29, s29, 0
	s_cmp_gt_u32 s30, 29
	s_mov_b64 s[0:1], s[2:3]
	s_cbranch_scc0 .LBB0_232
	s_and_b64 vcc, exec, s[44:45]
	s_cbranch_vccz .LBB0_235

; #define PG8_WAIT_V(n) asm volatile("s_waitcnt vmcnt(" #n ")" ::: "memory")
; #define PG8_BAR __builtin_amdgcn_s_barrier()
; template <class Epi, class Sched, bool ALIGN_EPI = false, bool SP2 = false>
; __device__ __forceinline__ void gemm_phase(PG8_LAS unsigned char* lds, const Gemm g, const Sched& S, const Epi& E) {
;     ...
;     PG8_WAIT_V(0);
;     if constexpr (!ALIGN_EPI) { if (wr == 0) PG8_BAR; }
;     PG8_BAR;
.LBB0_278:
	s_waitcnt vmcnt(0)
	v_readlane_b32 s4, v243, 2
	v_readlane_b32 s5, v243, 3
	s_movk_i32 s48, 0x2000
	s_movk_i32 s49, 0x3000
	s_movk_i32 s46, 0x1ff
	v_readlane_b32 s50, v241, 17
	s_mov_b32 s51, 0xd800000
	v_readlane_b32 s36, v241, 48
	s_cmp_lg_u32 s98, 0
	s_cbranch_scc1 .Lna_0
	s_barrier
.Lna_0:
	s_barrier
	v_readlane_b32 s6, v243, 4
	v_readlane_b32 s7, v243, 5
	v_readlane_b32 s8, v243, 6
	v_readlane_b32 s9, v243, 7
	v_readlane_b32 s10, v243, 8
	v_readlane_b32 s11, v243, 9
	v_readlane_b32 s12, v243, 10
	v_readlane_b32 s13, v243, 11
	v_readlane_b32 s14, v243, 12
	v_readlane_b32 s15, v243, 13
	v_readlane_b32 s16, v243, 14
	v_readlane_b32 s17, v243, 15
	v_readlane_b32 s18, v243, 16
	v_readlane_b32 s19, v243, 17

; #define PG8_STAGE(bufoff, gbase, voff) do { const char* gb_ = (const char*)(gbase); asm volatile("" : "+s"(gb_)); _Pragma("unroll") for (int _i = 0; _i < 2; ++_i) { unsigned vo_ = (voff)[_i]; asm volatile("" : "+v"(vo_));        \
;         __builtin_amdgcn_global_load_lds((const unsigned*)(gb_ + vo_), (PG8_LAS unsigned*)(lds + (bufoff) + ldsw + _i * 8192), 16, 0, 0); } } while (0)
; #define PG8_LDA(dst, b, h) do { _Pragma("unroll") for (int m = 0; m < 4; ++m) _Pragma("unroll") for (int k = 0; k < 2; ++k) dst[m][k] = *(const PG8_LAS bf16x8*)(lds + PG8_SA(b, h) + aoff + m * 2048 + k * 1024); } while (0)
; #define PG8_LDB(dst, b, h) do { _Pragma("unroll") for (int n = 0; n < 2; ++n) _Pragma("unroll") for (int k = 0; k < 2; ++k) dst[n][k] = *(const PG8_LAS bf16x8*)(lds + PG8_SB(b, h) + boff + n * 2048 + k * 1024); } while (0)
; #define PG8_MMA(ai, bj, At, Bt) do { __builtin_amdgcn_s_setprio(1); _Pragma("unroll") for (int m = 0; m < 4; ++m) _Pragma("unroll") for (int n = 0; n < 2; ++n) _Pragma("unroll") for (int k = 0; k < 2; ++k) \
;         acc[ai][bj][m][n] = __builtin_amdgcn_mfma_f32_16x16x32_bf16(Bt[n][k], At[m][k], acc[ai][bj][m][n], 0, 0, 0); __builtin_amdgcn_s_setprio(0); } while (0)
; #define PG8_WAIT_V(n) asm volatile("s_waitcnt vmcnt(" #n ")" ::: "memory")
; template <class Epi, class Sched, bool ALIGN_EPI = false, bool SP2 = false>
; __device__ __forceinline__ void gemm_phase(PG8_LAS unsigned char* lds, const Gemm g, const Sched& S, const Epi& E) {
;     ...
;             const bool last = (t == nt - 2);
;             const char* a1 = cA + (size_t)(t + 1) * kstep;
;             const char* a2 = last ? nA : cA + (size_t)(t + 2) * kstep; const char* b2 = last ? nB : cB + (size_t)(t + 2) * kstep;
;             const char* a3 = a2 + kstep; const char* b3 = b2 + kstep;
;             if (last && has_next) S.a_ready(nxt);
;             if constexpr (SP2) {
;             PG8_LDB(B0, 0, 0); PG8_LDB(B1, 0, 1); PG8_SCHED; PG8_LDA(At, 0, 0); PG8_STAGE(PG8_SA(1, 1), a1 + hstep, voffA);
;             PG8_WAIT_V(8); PG8_WAIT_L(0); PG8_BAR; PG8_MMA(0, 0, At, B0); PG8_MMA(0, 1, At, B1); PG8_BAR; PG8_SCHED;
;             PG8_LDA(At, 0, 1); PG8_STAGE(PG8_SB(0, 0), b2, voffB); PG8_STAGE(PG8_SB(0, 1), b2 + hstep, voffB); PG8_STAGE(PG8_SA(0, 0), a2, voffA);
;             PG8_WAIT_V(8); PG8_WAIT_L(0); PG8_BAR; PG8_MMA(1, 0, At, B0); PG8_MMA(1, 1, At, B1); PG8_BAR; PG8_SCHED;
.LBB0_634:
	s_add_u32 s16, s14, 0x100
	s_addc_u32 s17, s15, 0
	s_cmp_eq_u32 s53, 28
	s_cselect_b32 s22, s49, s16
	s_cselect_b32 s23, s7, s17
	s_cselect_b32 s20, s50, s51
	s_cselect_b32 s21, s5, s52
	s_add_u32 s18, s22, 0x80
	s_addc_u32 s19, s23, 0
	s_add_i32 s54, 0, 0x10000
	s_add_i32 s55, 0, 0x14000
	ds_read_b128 v[82:85], v244
	ds_read_b128 v[86:89], v244 offset:1024
	ds_read_b128 v[90:93], v244 offset:2048
	ds_read_b128 v[94:97], v244 offset:3072
	ds_read_b128 v[146:149], v244 offset:16384
	ds_read_b128 v[150:153], v244 offset:17408
	ds_read_b128 v[154:157], v244 offset:18432
	ds_read_b128 v[158:161], v244 offset:19456
	s_add_u32 s14, s14, 0x80080
	s_addc_u32 s15, s15, 0
	ds_read_b128 v[178:181], v188
	ds_read_b128 v[190:193], v188 offset:1024
	ds_read_b128 v[194:197], v188 offset:2048
	ds_read_b128 v[198:201], v188 offset:3072
	ds_read_b128 v[202:205], v188 offset:4096
	ds_read_b128 v[206:209], v188 offset:5120
	ds_read_b128 v[210:213], v188 offset:6144
	ds_read_b128 v[220:223], v188 offset:7168
	s_add_i32 m0, s27, 0xc000
	s_nop 0
	global_load_lds_dwordx4 v1, s[14:15]
	s_add_i32 m0, s27, 0xe000
	s_nop 0
	global_load_lds_dwordx4 v164, s[14:15]
	s_waitcnt vmcnt(8)
	s_waitcnt lgkmcnt(0)
	s_barrier
	s_setprio 1
	s_waitcnt lgkmcnt(0)
	v_mfma_f32_16x16x32_bf16 v[142:145], v[82:85], v[178:181], v[142:145]
	v_mfma_f32_16x16x32_bf16 v[142:145], v[86:89], v[190:193], v[142:145]
	v_mfma_f32_16x16x32_bf16 v[126:129], v[82:85], v[194:197], v[126:129]
	v_mfma_f32_16x16x32_bf16 v[126:129], v[86:89], v[198:201], v[126:129]
	v_mfma_f32_16x16x32_bf16 v[110:113], v[82:85], v[202:205], v[110:113]
	v_mfma_f32_16x16x32_bf16 v[110:113], v[86:89], v[206:209], v[110:113]
	v_mfma_f32_16x16x32_bf16 v[78:81], v[82:85], v[210:213], v[78:81]
	v_mfma_f32_16x16x32_bf16 v[78:81], v[86:89], v[220:223], v[78:81]
	v_mfma_f32_16x16x32_bf16 v[138:141], v[90:93], v[178:181], v[138:141]
	v_mfma_f32_16x16x32_bf16 v[138:141], v[94:97], v[190:193], v[138:141]
	v_mfma_f32_16x16x32_bf16 v[122:125], v[90:93], v[194:197], v[122:125]
	v_mfma_f32_16x16x32_bf16 v[122:125], v[94:97], v[198:201], v[122:125]
	v_mfma_f32_16x16x32_bf16 v[106:109], v[90:93], v[202:205], v[106:109]
	v_mfma_f32_16x16x32_bf16 v[106:109], v[94:97], v[206:209], v[106:109]
	v_mfma_f32_16x16x32_bf16 v[74:77], v[90:93], v[210:213], v[74:77]
	v_mfma_f32_16x16x32_bf16 v[74:77], v[94:97], v[220:223], v[74:77]
	s_setprio 0
	s_setprio 1
	v_mfma_f32_16x16x32_bf16 v[134:137], v[146:149], v[178:181], v[134:137]
	v_mfma_f32_16x16x32_bf16 v[134:137], v[150:153], v[190:193], v[134:137]
	v_mfma_f32_16x16x32_bf16 v[118:121], v[146:149], v[194:197], v[118:121]
	v_mfma_f32_16x16x32_bf16 v[118:121], v[150:153], v[198:201], v[118:121]
	v_mfma_f32_16x16x32_bf16 v[102:105], v[146:149], v[202:205], v[102:105]
	v_mfma_f32_16x16x32_bf16 v[102:105], v[150:153], v[206:209], v[102:105]
	v_mfma_f32_16x16x32_bf16 v[70:73], v[146:149], v[210:213], v[70:73]
	v_mfma_f32_16x16x32_bf16 v[70:73], v[150:153], v[220:223], v[70:73]
	v_mfma_f32_16x16x32_bf16 v[130:133], v[154:157], v[178:181], v[130:133]
	v_mfma_f32_16x16x32_bf16 v[130:133], v[158:161], v[190:193], v[130:133]
	v_mfma_f32_16x16x32_bf16 v[114:117], v[154:157], v[194:197], v[114:117]
	v_mfma_f32_16x16x32_bf16 v[114:117], v[158:161], v[198:201], v[114:117]
	v_mfma_f32_16x16x32_bf16 v[98:101], v[154:157], v[202:205], v[98:101]
	v_mfma_f32_16x16x32_bf16 v[98:101], v[158:161], v[206:209], v[98:101]
	v_mfma_f32_16x16x32_bf16 v[66:69], v[154:157], v[210:213], v[66:69]
	v_mfma_f32_16x16x32_bf16 v[66:69], v[158:161], v[220:223], v[66:69]
	s_setprio 0
	s_barrier
	s_mov_b64 s[14:15], s[20:21]
	s_add_i32 s54, s54, s26
	ds_read_b128 v[178:181], v188 offset:16384
	ds_read_b128 v[190:193], v188 offset:17408
	ds_read_b128 v[194:197], v188 offset:18432
	ds_read_b128 v[198:201], v188 offset:19456
	ds_read_b128 v[202:205], v188 offset:20480
	ds_read_b128 v[206:209], v188 offset:21504
	ds_read_b128 v[210:213], v188 offset:22528
	ds_read_b128 v[220:223], v188 offset:23552
	s_mov_b32 m0, s54
	s_nop 0
	global_load_lds_dwordx4 v162, s[14:15]
	s_add_i32 m0, s54, 0x2000
	s_nop 0
	global_load_lds_dwordx4 v184, s[14:15]
	s_add_u32 s14, s20, 0x80000
	s_addc_u32 s15, s21, 0
	s_add_i32 s54, s55, s26
	s_mov_b32 m0, s54
	s_nop 0
	global_load_lds_dwordx4 v162, s[14:15]
	s_add_i32 m0, s54, 0x2000
	s_nop 0
	global_load_lds_dwordx4 v184, s[14:15]
	s_mov_b64 s[14:15], s[22:23]
	s_mov_b32 m0, s27
	s_nop 0
	global_load_lds_dwordx4 v1, s[14:15]
	s_mov_b32 m0, s28
	s_nop 0
	global_load_lds_dwordx4 v164, s[14:15]
	s_waitcnt vmcnt(8)
	s_waitcnt lgkmcnt(0)
	s_barrier
; #define PG8_STAGE(bufoff, gbase, voff) do { const char* gb_ = (const char*)(gbase); asm volatile("" : "+s"(gb_)); _Pragma("unroll") for (int _i = 0; _i < 2; ++_i) { unsigned vo_ = (voff)[_i]; asm volatile("" : "+v"(vo_));        \
;         __builtin_amdgcn_global_load_lds((const unsigned*)(gb_ + vo_), (PG8_LAS unsigned*)(lds + (bufoff) + ldsw + _i * 8192), 16, 0, 0); } } while (0)
; #define PG8_LDA(dst, b, h) do { _Pragma("unroll") for (int m = 0; m < 4; ++m) _Pragma("unroll") for (int k = 0; k < 2; ++k) dst[m][k] = *(const PG8_LAS bf16x8*)(lds + PG8_SA(b, h) + aoff + m * 2048 + k * 1024); } while (0)
; #define PG8_LDB(dst, b, h) do { _Pragma("unroll") for (int n = 0; n < 2; ++n) _Pragma("unroll") for (int k = 0; k < 2; ++k) dst[n][k] = *(const PG8_LAS bf16x8*)(lds + PG8_SB(b, h) + boff + n * 2048 + k * 1024); } while (0)
; #define PG8_MMA(ai, bj, At, Bt) do { __builtin_amdgcn_s_setprio(1); _Pragma("unroll") for (int m = 0; m < 4; ++m) _Pragma("unroll") for (int n = 0; n < 2; ++n) _Pragma("unroll") for (int k = 0; k < 2; ++k) \
;         acc[ai][bj][m][n] = __builtin_amdgcn_mfma_f32_16x16x32_bf16(Bt[n][k], At[m][k], acc[ai][bj][m][n], 0, 0, 0); __builtin_amdgcn_s_setprio(0); } while (0)
; #define PG8_WAIT_V(n) asm volatile("s_waitcnt vmcnt(" #n ")" ::: "memory")
; #define PG8_WAIT_L(n) asm volatile("s_waitcnt lgkmcnt(" #n ")" ::: "memory")
; #define PG8_BAR __builtin_amdgcn_s_barrier()
; #define PG8_SCHED __builtin_amdgcn_sched_barrier(0)
; template <class Epi, class Sched, bool ALIGN_EPI = false, bool SP2 = false>
; __device__ __forceinline__ void gemm_phase(PG8_LAS unsigned char* lds, const Gemm g, const Sched& S, const Epi& E) {
;     ...
;             PG8_WAIT_V(8); PG8_WAIT_L(0); PG8_BAR; PG8_MMA(1, 0, At, B0); PG8_MMA(1, 1, At, B1); PG8_BAR; PG8_SCHED;
;             PG8_LDB(B0, 1, 0); PG8_LDB(B1, 1, 1); PG8_SCHED; PG8_LDA(At, 1, 0); PG8_STAGE(PG8_SA(0, 1), a2 + hstep, voffA);
;             PG8_WAIT_V(8); PG8_WAIT_L(0); PG8_BAR; PG8_MMA(0, 0, At, B0); PG8_MMA(0, 1, At, B1); PG8_BAR; PG8_SCHED;
	s_setprio 1
	s_waitcnt lgkmcnt(0)
	v_mfma_f32_16x16x32_bf16 v[62:65], v[82:85], v[178:181], v[62:65]
	v_mfma_f32_16x16x32_bf16 v[62:65], v[86:89], v[190:193], v[62:65]
	v_mfma_f32_16x16x32_bf16 v[46:49], v[82:85], v[194:197], v[46:49]
	v_mfma_f32_16x16x32_bf16 v[46:49], v[86:89], v[198:201], v[46:49]
	v_mfma_f32_16x16x32_bf16 v[30:33], v[82:85], v[202:205], v[30:33]
	v_mfma_f32_16x16x32_bf16 v[30:33], v[86:89], v[206:209], v[30:33]
	v_mfma_f32_16x16x32_bf16 v[14:17], v[82:85], v[210:213], v[14:17]
	v_mfma_f32_16x16x32_bf16 v[14:17], v[86:89], v[220:223], v[14:17]
	v_mfma_f32_16x16x32_bf16 v[58:61], v[90:93], v[178:181], v[58:61]
	v_mfma_f32_16x16x32_bf16 v[58:61], v[94:97], v[190:193], v[58:61]
	v_mfma_f32_16x16x32_bf16 v[42:45], v[90:93], v[194:197], v[42:45]
	v_mfma_f32_16x16x32_bf16 v[42:45], v[94:97], v[198:201], v[42:45]
	v_mfma_f32_16x16x32_bf16 v[26:29], v[90:93], v[202:205], v[26:29]
	v_mfma_f32_16x16x32_bf16 v[26:29], v[94:97], v[206:209], v[26:29]
	v_mfma_f32_16x16x32_bf16 v[10:13], v[90:93], v[210:213], v[10:13]
	v_mfma_f32_16x16x32_bf16 v[10:13], v[94:97], v[220:223], v[10:13]
	s_setprio 0
	s_setprio 1
	v_mfma_f32_16x16x32_bf16 v[54:57], v[146:149], v[178:181], v[54:57]
	v_mfma_f32_16x16x32_bf16 v[54:57], v[150:153], v[190:193], v[54:57]
	v_mfma_f32_16x16x32_bf16 v[38:41], v[146:149], v[194:197], v[38:41]
	v_mfma_f32_16x16x32_bf16 v[38:41], v[150:153], v[198:201], v[38:41]
	v_mfma_f32_16x16x32_bf16 v[22:25], v[146:149], v[202:205], v[22:25]
	v_mfma_f32_16x16x32_bf16 v[22:25], v[150:153], v[206:209], v[22:25]
	v_mfma_f32_16x16x32_bf16 v[6:9], v[146:149], v[210:213], v[6:9]
	v_mfma_f32_16x16x32_bf16 v[6:9], v[150:153], v[220:223], v[6:9]
	v_mfma_f32_16x16x32_bf16 v[50:53], v[154:157], v[178:181], v[50:53]
	v_mfma_f32_16x16x32_bf16 v[50:53], v[158:161], v[190:193], v[50:53]
	v_mfma_f32_16x16x32_bf16 v[34:37], v[154:157], v[194:197], v[34:37]
	v_mfma_f32_16x16x32_bf16 v[34:37], v[158:161], v[198:201], v[34:37]
	v_mfma_f32_16x16x32_bf16 v[18:21], v[154:157], v[202:205], v[18:21]
	v_mfma_f32_16x16x32_bf16 v[18:21], v[158:161], v[206:209], v[18:21]
	v_mfma_f32_16x16x32_bf16 v[2:5], v[154:157], v[210:213], v[2:5]
	v_mfma_f32_16x16x32_bf16 v[2:5], v[158:161], v[220:223], v[2:5]
	s_setprio 0
	s_barrier
	s_add_i32 s54, 0, 0x18000
	s_add_i32 s55, 0, 0x1c000
	ds_read_b128 v[82:85], v244 offset:32768
	ds_read_b128 v[86:89], v244 offset:33792
	ds_read_b128 v[90:93], v244 offset:34816
	ds_read_b128 v[94:97], v244 offset:35840
	ds_read_b128 v[146:149], v244 offset:49152
	ds_read_b128 v[150:153], v244 offset:50176
	ds_read_b128 v[154:157], v244 offset:51200
	ds_read_b128 v[158:161], v244 offset:52224
	s_add_u32 s14, s22, 0x80000
	s_addc_u32 s15, s23, 0
	s_mov_b32 m0, s29
	ds_read_b128 v[178:181], v188 offset:32768
	ds_read_b128 v[190:193], v188 offset:33792
	ds_read_b128 v[194:197], v188 offset:34816
	ds_read_b128 v[198:201], v188 offset:35840
	ds_read_b128 v[202:205], v188 offset:36864
	ds_read_b128 v[206:209], v188 offset:37888
	ds_read_b128 v[210:213], v188 offset:38912
	ds_read_b128 v[220:223], v188 offset:39936
	s_nop 0
	global_load_lds_dwordx4 v1, s[14:15]
	s_mov_b32 m0, s33
	s_nop 0
	global_load_lds_dwordx4 v164, s[14:15]
	s_waitcnt vmcnt(8)
	s_waitcnt lgkmcnt(0)
	s_barrier
	s_setprio 1
	s_waitcnt lgkmcnt(0)
	v_mfma_f32_16x16x32_bf16 v[142:145], v[82:85], v[178:181], v[142:145]
	v_mfma_f32_16x16x32_bf16 v[142:145], v[86:89], v[190:193], v[142:145]
	v_mfma_f32_16x16x32_bf16 v[126:129], v[82:85], v[194:197], v[126:129]
	v_mfma_f32_16x16x32_bf16 v[126:129], v[86:89], v[198:201], v[126:129]
	v_mfma_f32_16x16x32_bf16 v[110:113], v[82:85], v[202:205], v[110:113]
	v_mfma_f32_16x16x32_bf16 v[110:113], v[86:89], v[206:209], v[110:113]
	v_mfma_f32_16x16x32_bf16 v[78:81], v[82:85], v[210:213], v[78:81]
	v_mfma_f32_16x16x32_bf16 v[78:81], v[86:89], v[220:223], v[78:81]
	v_mfma_f32_16x16x32_bf16 v[138:141], v[90:93], v[178:181], v[138:141]
	v_mfma_f32_16x16x32_bf16 v[138:141], v[94:97], v[190:193], v[138:141]
	v_mfma_f32_16x16x32_bf16 v[122:125], v[90:93], v[194:197], v[122:125]
	v_mfma_f32_16x16x32_bf16 v[122:125], v[94:97], v[198:201], v[122:125]
	v_mfma_f32_16x16x32_bf16 v[106:109], v[90:93], v[202:205], v[106:109]
	v_mfma_f32_16x16x32_bf16 v[106:109], v[94:97], v[206:209], v[106:109]
	v_mfma_f32_16x16x32_bf16 v[74:77], v[90:93], v[210:213], v[74:77]
	v_mfma_f32_16x16x32_bf16 v[74:77], v[94:97], v[220:223], v[74:77]
	s_setprio 0
	s_setprio 1
	v_mfma_f32_16x16x32_bf16 v[134:137], v[146:149], v[178:181], v[134:137]
	v_mfma_f32_16x16x32_bf16 v[134:137], v[150:153], v[190:193], v[134:137]
	v_mfma_f32_16x16x32_bf16 v[118:121], v[146:149], v[194:197], v[118:121]
	v_mfma_f32_16x16x32_bf16 v[118:121], v[150:153], v[198:201], v[118:121]
	v_mfma_f32_16x16x32_bf16 v[102:105], v[146:149], v[202:205], v[102:105]
	v_mfma_f32_16x16x32_bf16 v[102:105], v[150:153], v[206:209], v[102:105]
	v_mfma_f32_16x16x32_bf16 v[70:73], v[146:149], v[210:213], v[70:73]
	v_mfma_f32_16x16x32_bf16 v[70:73], v[150:153], v[220:223], v[70:73]
	v_mfma_f32_16x16x32_bf16 v[130:133], v[154:157], v[178:181], v[130:133]
	v_mfma_f32_16x16x32_bf16 v[130:133], v[158:161], v[190:193], v[130:133]
	v_mfma_f32_16x16x32_bf16 v[114:117], v[154:157], v[194:197], v[114:117]
	v_mfma_f32_16x16x32_bf16 v[114:117], v[158:161], v[198:201], v[114:117]
	v_mfma_f32_16x16x32_bf16 v[98:101], v[154:157], v[202:205], v[98:101]
	v_mfma_f32_16x16x32_bf16 v[98:101], v[158:161], v[206:209], v[98:101]
	v_mfma_f32_16x16x32_bf16 v[66:69], v[154:157], v[210:213], v[66:69]
	v_mfma_f32_16x16x32_bf16 v[66:69], v[158:161], v[220:223], v[66:69]
	s_setprio 0
	s_barrier
; #define PG8_STAGE(bufoff, gbase, voff) do { const char* gb_ = (const char*)(gbase); asm volatile("" : "+s"(gb_)); _Pragma("unroll") for (int _i = 0; _i < 2; ++_i) { unsigned vo_ = (voff)[_i]; asm volatile("" : "+v"(vo_));        \
;         __builtin_amdgcn_global_load_lds((const unsigned*)(gb_ + vo_), (PG8_LAS unsigned*)(lds + (bufoff) + ldsw + _i * 8192), 16, 0, 0); } } while (0)
; #define PG8_LDA(dst, b, h) do { _Pragma("unroll") for (int m = 0; m < 4; ++m) _Pragma("unroll") for (int k = 0; k < 2; ++k) dst[m][k] = *(const PG8_LAS bf16x8*)(lds + PG8_SA(b, h) + aoff + m * 2048 + k * 1024); } while (0)
; #define PG8_MMA(ai, bj, At, Bt) do { __builtin_amdgcn_s_setprio(1); _Pragma("unroll") for (int m = 0; m < 4; ++m) _Pragma("unroll") for (int n = 0; n < 2; ++n) _Pragma("unroll") for (int k = 0; k < 2; ++k) \
;         acc[ai][bj][m][n] = __builtin_amdgcn_mfma_f32_16x16x32_bf16(Bt[n][k], At[m][k], acc[ai][bj][m][n], 0, 0, 0); __builtin_amdgcn_s_setprio(0); } while (0)
; #define PG8_WAIT_V(n) asm volatile("s_waitcnt vmcnt(" #n ")" ::: "memory")
; #define PG8_WAIT_L(n) asm volatile("s_waitcnt lgkmcnt(" #n ")" ::: "memory")
; #define PG8_BAR __builtin_amdgcn_s_barrier()
; #define PG8_SCHED __builtin_amdgcn_sched_barrier(0)
; template <class Epi, class Sched, bool ALIGN_EPI = false, bool SP2 = false>
; __device__ __forceinline__ void gemm_phase(PG8_LAS unsigned char* lds, const Gemm g, const Sched& S, const Epi& E) {
;     ...
;             PG8_LDA(At, 1, 1); PG8_STAGE(PG8_SB(1, 0), b3, voffB); PG8_STAGE(PG8_SB(1, 1), b3 + hstep, voffB); PG8_STAGE(PG8_SA(1, 0), a3, voffA);
;             PG8_WAIT_V(8); PG8_WAIT_L(0); PG8_BAR; PG8_MMA(1, 0, At, B0); PG8_MMA(1, 1, At, B1); PG8_BAR; PG8_SCHED;
	s_add_u32 s14, s20, 0x80
	s_addc_u32 s15, s21, 0
	s_add_i32 s22, s54, s26
	ds_read_b128 v[178:181], v188 offset:49152
	ds_read_b128 v[190:193], v188 offset:50176
	ds_read_b128 v[194:197], v188 offset:51200
	ds_read_b128 v[198:201], v188 offset:52224
	ds_read_b128 v[202:205], v188 offset:53248
	ds_read_b128 v[206:209], v188 offset:54272
	ds_read_b128 v[210:213], v188 offset:55296
	ds_read_b128 v[220:223], v188 offset:56320
	s_mov_b32 m0, s22
	s_nop 0
	global_load_lds_dwordx4 v162, s[14:15]
	s_add_i32 m0, s22, 0x2000
	s_nop 0
	global_load_lds_dwordx4 v184, s[14:15]
	s_add_u32 s14, s20, 0x80080
	s_addc_u32 s15, s21, 0
	s_add_i32 s20, s55, s26
	s_mov_b32 m0, s20
	s_nop 0
	global_load_lds_dwordx4 v162, s[14:15]
	s_add_i32 m0, s20, 0x2000
	s_nop 0
	global_load_lds_dwordx4 v184, s[14:15]
	s_mov_b32 m0, s38
	s_nop 0
	global_load_lds_dwordx4 v1, s[18:19]
	s_mov_b32 m0, s39
	s_nop 0
	global_load_lds_dwordx4 v164, s[18:19]
	s_waitcnt vmcnt(8)
	s_waitcnt lgkmcnt(0)
	s_barrier
	s_setprio 1
	s_waitcnt lgkmcnt(0)
	v_mfma_f32_16x16x32_bf16 v[62:65], v[82:85], v[178:181], v[62:65]
	v_mfma_f32_16x16x32_bf16 v[62:65], v[86:89], v[190:193], v[62:65]
	v_mfma_f32_16x16x32_bf16 v[46:49], v[82:85], v[194:197], v[46:49]
	v_mfma_f32_16x16x32_bf16 v[46:49], v[86:89], v[198:201], v[46:49]
	v_mfma_f32_16x16x32_bf16 v[30:33], v[82:85], v[202:205], v[30:33]
	v_mfma_f32_16x16x32_bf16 v[30:33], v[86:89], v[206:209], v[30:33]
	v_mfma_f32_16x16x32_bf16 v[14:17], v[82:85], v[210:213], v[14:17]
	v_mfma_f32_16x16x32_bf16 v[14:17], v[86:89], v[220:223], v[14:17]
	v_mfma_f32_16x16x32_bf16 v[58:61], v[90:93], v[178:181], v[58:61]
	v_mfma_f32_16x16x32_bf16 v[58:61], v[94:97], v[190:193], v[58:61]
	v_mfma_f32_16x16x32_bf16 v[42:45], v[90:93], v[194:197], v[42:45]
	v_mfma_f32_16x16x32_bf16 v[42:45], v[94:97], v[198:201], v[42:45]
	v_mfma_f32_16x16x32_bf16 v[26:29], v[90:93], v[202:205], v[26:29]
	v_mfma_f32_16x16x32_bf16 v[26:29], v[94:97], v[206:209], v[26:29]
	v_mfma_f32_16x16x32_bf16 v[10:13], v[90:93], v[210:213], v[10:13]
	v_mfma_f32_16x16x32_bf16 v[10:13], v[94:97], v[220:223], v[10:13]
	s_setprio 0
	s_setprio 1
	v_mfma_f32_16x16x32_bf16 v[54:57], v[146:149], v[178:181], v[54:57]
	v_mfma_f32_16x16x32_bf16 v[54:57], v[150:153], v[190:193], v[54:57]
	v_mfma_f32_16x16x32_bf16 v[38:41], v[146:149], v[194:197], v[38:41]
	v_mfma_f32_16x16x32_bf16 v[38:41], v[150:153], v[198:201], v[38:41]
	v_mfma_f32_16x16x32_bf16 v[22:25], v[146:149], v[202:205], v[22:25]
	v_mfma_f32_16x16x32_bf16 v[22:25], v[150:153], v[206:209], v[22:25]
	v_mfma_f32_16x16x32_bf16 v[6:9], v[146:149], v[210:213], v[6:9]
	v_mfma_f32_16x16x32_bf16 v[6:9], v[150:153], v[220:223], v[6:9]
	v_mfma_f32_16x16x32_bf16 v[50:53], v[154:157], v[178:181], v[50:53]
	v_mfma_f32_16x16x32_bf16 v[50:53], v[158:161], v[190:193], v[50:53]
	v_mfma_f32_16x16x32_bf16 v[34:37], v[154:157], v[194:197], v[34:37]
	v_mfma_f32_16x16x32_bf16 v[34:37], v[158:161], v[198:201], v[34:37]
	v_mfma_f32_16x16x32_bf16 v[18:21], v[154:157], v[202:205], v[18:21]
	v_mfma_f32_16x16x32_bf16 v[18:21], v[158:161], v[206:209], v[18:21]
	v_mfma_f32_16x16x32_bf16 v[2:5], v[154:157], v[210:213], v[2:5]
	v_mfma_f32_16x16x32_bf16 v[2:5], v[158:161], v[220:223], v[2:5]
	s_setprio 0
	s_barrier
	s_add_i32 s53, s53, 2
	s_add_u32 s51, s51, 0x100
	s_addc_u32 s52, s52, 0
	s_cmp_gt_u32 s53, 29
	s_mov_b64 s[14:15], s[16:17]
	s_cbranch_scc0 .LBB0_634
	s_and_b64 vcc, exec, s[2:3]
	s_cbranch_vccz .LBB0_637

; #define PG8_WAIT_V(n) asm volatile("s_waitcnt vmcnt(" #n ")" ::: "memory")
; #define PG8_BAR __builtin_amdgcn_s_barrier()
; template <class Epi, class Sched, bool ALIGN_EPI = false, bool SP2 = false>
; __device__ __forceinline__ void gemm_phase(PG8_LAS unsigned char* lds, const Gemm g, const Sched& S, const Epi& E) {
;     ...
;     PG8_WAIT_V(0);
;     if constexpr (!ALIGN_EPI) { if (wr == 0) PG8_BAR; }
;     PG8_BAR;
.LBB0_640:
	s_waitcnt vmcnt(0)
	v_readlane_b32 s4, v243, 2
	v_readlane_b32 s5, v243, 3
	s_movk_i32 s48, 0x2000
	s_movk_i32 s46, 0x1ff
	s_cmp_lg_u32 s98, 0
	s_cbranch_scc1 .Lna_1
	s_barrier
.Lna_1:
	s_barrier
	v_readlane_b32 s6, v243, 4
	v_readlane_b32 s7, v243, 5
	v_readlane_b32 s8, v243, 6
	v_readlane_b32 s9, v243, 7
	v_readlane_b32 s10, v243, 8
	v_readlane_b32 s11, v243, 9
	v_readlane_b32 s12, v243, 10
	v_readlane_b32 s13, v243, 11
	v_readlane_b32 s14, v243, 12
	v_readlane_b32 s15, v243, 13
	v_readlane_b32 s16, v243, 14
	v_readlane_b32 s17, v243, 15
	v_readlane_b32 s18, v243, 16
	v_readlane_b32 s19, v243, 17
	v_readlane_b32 s40, v241, 42
